# next-step LDS fragment reads moved after the second post-barrier DMA piece
# speedup vs baseline: 1.0137x; 1.0021x over previous
; DI f32x16 mfma(bf16x8 a, bf16x8 b, f32x16 c) { return __builtin_amdgcn_mfma_f32_32x32x16_bf16(a, b, c, 0, 0, 0); }
; template <int BK> DI int swz(int row) { constexpr int CPR = BK / 8; return (row / (16 / CPR)) % CPR; }
; DI void wait_vm0() { asm volatile("s_waitcnt vmcnt(0)" ::: "memory"); }
;   DI void pre(int grow0, int gcol0, int lane, int w, char* lds) { xpass(0, grow0, gcol0, lane, w, lds); }
;     ...
;   for (int kt = 0; kt < nk; ++kt) {
;     char* cur = lds + (kt & 1) * STG; char* nxt = lds + ((kt + 1) & 1) * STG;
;     const bool more = kt + 1 < nk;
;     const bf16_t* An = Ag + (kt + 1) * BK; const bf16_t* Bn = Bg + (kt + 1) * BK;
;     if (!more) epi.pre(row0 + wm * 64, col0 + wn * (32 * NTW), lane, w, lds);
;     bf16x8 fa[2][2], fb[2][NTW];
; #pragma unroll
;     for (int mt = 0; mt < 2; ++mt) { int row = wm * 64 + mt * 32 + l31; fa[0][mt] = *(const bf16x8*)(cur + row * (BK * 2) + ((hh ^ swz<BK>(row)) << 4)); }
; #pragma unroll
;     for (int nt = 0; nt < NTW; ++nt) { int row = wn * (32 * NTW) + nt * 32 + l31; fb[0][nt] = *(const bf16x8*)(cur + ABYTES + row * (BK * 2) + ((hh ^ swz<BK>(row)) << 4)); }
; #pragma unroll
;     for (int kk = 0; kk < NKK; ++kk) {
;       if (kk + 1 < NKK) {
;         const int ch = (kk + 1) * 2 + hh;
; #pragma unroll
;         for (int mt = 0; mt < 2; ++mt) { int row = wm * 64 + mt * 32 + l31; fa[(kk + 1) & 1][mt] = *(const bf16x8*)(cur + row * (BK * 2) + ((ch ^ swz<BK>(row)) << 4)); }
; #pragma unroll
;         for (int nt = 0; nt < NTW; ++nt) { int row = wn * (32 * NTW) + nt * 32 + l31; fb[(kk + 1) & 1][nt] = *(const bf16x8*)(cur + ABYTES + row * (BK * 2) + ((ch ^ swz<BK>(row)) << 4)); }
;       }
;       if (more) {
; #pragma unroll
;         for (int q = 0; q < PPK; ++q) {
;           const int pi = kk * PPK + q;
;           if (pi < NPA) stage_piece<BM, BK>(An, lda, nxt, tid, pi, wv);
;           else if (pi < NP) stage_piece<BN, BK>(Bn, ldb, nxt + ABYTES, tid, pi - NPA, wv);
;         }
;       }
;       __builtin_amdgcn_s_setprio(1);
; #pragma unroll
;       for (int mt = 0; mt < 2; ++mt)
; #pragma unroll
;         for (int nt = 0; nt < NTW; ++nt) acc[mt][nt] = mfma(fa[kk & 1][mt], fb[kk & 1][nt], acc[mt][nt]);
;       __builtin_amdgcn_s_setprio(0);
;       __builtin_amdgcn_sched_barrier(0);
;     }
;     wait_vm0();
;     __syncthreads();
.LBB0_173:
	s_and_b32 s30, s3, 0x10000
	s_xor_b32 s100, s30, 0x10000
	v_add3_u32 v194, s100, v136, v166
	v_add3_u32 v198, s100, v144, v167
	ds_read_b128 v[194:197], v194
	v_add3_u32 v202, s100, v145, v161
	ds_read_b128 v[198:201], v198
	v_add3_u32 v206, s100, v152, v163
	ds_read_b128 v[202:205], v202 offset:32768
	v_add3_u32 v210, s100, v155, v159
	ds_read_b128 v[206:209], v206 offset:32768
	v_add3_u32 v226, s100, v158, v160
	ds_read_b128 v[210:213], v210 offset:32768
	ds_read_b128 v[226:229], v226 offset:32768
	s_waitcnt lgkmcnt(6)
	s_mov_b32 m0, s31
	v_lshl_add_u64 v[232:233], v[214:215], 0, s[28:29]
	v_mfma_f32_32x32x16_bf16 v[114:129], v[170:173], v[178:181], v[114:129]
	global_load_lds_dwordx4 v[232:233], off
	s_add_i32 m0, s31, 0x2000
	v_lshl_add_u64 v[232:233], v[214:215], 0, s[24:25]
	v_mfma_f32_32x32x16_bf16 v[98:113], v[170:173], v[182:185], v[98:113]
	v_mfma_f32_32x32x16_bf16 v[82:97], v[170:173], v[186:189], v[82:97]
	global_load_lds_dwordx4 v[232:233], off
	s_add_i32 m0, s31, 0x4000
	v_lshl_add_u64 v[232:233], v[214:215], 0, s[26:27]
	v_mfma_f32_32x32x16_bf16 v[66:81], v[170:173], v[190:193], v[66:81]
	v_mfma_f32_32x32x16_bf16 v[50:65], v[174:177], v[178:181], v[50:65]
	global_load_lds_dwordx4 v[232:233], off
	s_add_i32 m0, s31, 0x6000
	v_lshl_add_u64 v[232:233], v[214:215], 0, s[38:39]
	v_mfma_f32_32x32x16_bf16 v[34:49], v[174:177], v[182:185], v[34:49]
	v_mfma_f32_32x32x16_bf16 v[18:33], v[174:177], v[186:189], v[18:33]
	global_load_lds_dwordx4 v[232:233], off
	v_mfma_f32_32x32x16_bf16 v[2:17], v[174:177], v[190:193], v[2:17]
	v_add3_u32 v170, s100, v136, v153
	v_add3_u32 v174, s100, v144, v154
	ds_read_b128 v[170:173], v170
	v_add3_u32 v178, s100, v145, v149
	ds_read_b128 v[174:177], v174
	v_add3_u32 v182, s100, v152, v150
	ds_read_b128 v[178:181], v178 offset:32768
	v_add3_u32 v186, s100, v155, v147
	ds_read_b128 v[182:185], v182 offset:32768
	v_add3_u32 v190, s100, v158, v148
	ds_read_b128 v[186:189], v186 offset:32768
	ds_read_b128 v[190:193], v190 offset:32768
	s_waitcnt lgkmcnt(6)
	v_mfma_f32_32x32x16_bf16 v[114:129], v[194:197], v[202:205], v[114:129]
	v_mfma_f32_32x32x16_bf16 v[98:113], v[194:197], v[206:209], v[98:113]
	v_mfma_f32_32x32x16_bf16 v[82:97], v[194:197], v[210:213], v[82:97]
	v_mfma_f32_32x32x16_bf16 v[66:81], v[194:197], v[226:229], v[66:81]
	v_mfma_f32_32x32x16_bf16 v[50:65], v[198:201], v[202:205], v[50:65]
	v_mfma_f32_32x32x16_bf16 v[34:49], v[198:201], v[206:209], v[34:49]
	v_mfma_f32_32x32x16_bf16 v[18:33], v[198:201], v[210:213], v[18:33]
	v_mfma_f32_32x32x16_bf16 v[2:17], v[198:201], v[226:229], v[2:17]
	v_add3_u32 v194, s100, v136, v141
	v_add3_u32 v198, s100, v144, v142
	ds_read_b128 v[194:197], v194
	v_add3_u32 v202, s100, v145, v139
	ds_read_b128 v[198:201], v198
	v_add3_u32 v206, s100, v152, v140
	ds_read_b128 v[202:205], v202 offset:32768
	v_add3_u32 v210, s100, v155, v137
	ds_read_b128 v[206:209], v206 offset:32768
	v_add3_u32 v226, s100, v158, v138
	ds_read_b128 v[210:213], v210 offset:32768
	ds_read_b128 v[226:229], v226 offset:32768
	s_waitcnt lgkmcnt(6)
	v_mfma_f32_32x32x16_bf16 v[114:129], v[170:173], v[178:181], v[114:129]
	v_mfma_f32_32x32x16_bf16 v[98:113], v[170:173], v[182:185], v[98:113]
	v_mfma_f32_32x32x16_bf16 v[82:97], v[170:173], v[186:189], v[82:97]
	v_mfma_f32_32x32x16_bf16 v[66:81], v[170:173], v[190:193], v[66:81]
	v_mfma_f32_32x32x16_bf16 v[50:65], v[174:177], v[178:181], v[50:65]
	v_mfma_f32_32x32x16_bf16 v[34:49], v[174:177], v[182:185], v[34:49]
	v_mfma_f32_32x32x16_bf16 v[18:33], v[174:177], v[186:189], v[18:33]
	v_mfma_f32_32x32x16_bf16 v[2:17], v[174:177], v[190:193], v[2:17]
	s_add_u32 s6, s6, 0x80
	s_addc_u32 s7, s7, 0
	s_add_i32 s3, s3, 0x10000
	s_waitcnt vmcnt(0) lgkmcnt(0)
	s_barrier
	s_cmpk_lg_i32 s6, 0x780
	s_cbranch_scc0 .Lk173_exit
	s_add_i32 s31, s100, s2
	v_lshl_add_u64 v[214:215], v[132:133], 0, s[6:7]
	v_lshl_add_u64 v[230:231], v[130:131], 0, s[6:7]
	s_add_i32 m0, s31, 0x8000
	v_lshl_add_u64 v[232:233], v[230:231], 0, s[28:29]
	v_mfma_f32_32x32x16_bf16 v[114:129], v[194:197], v[202:205], v[114:129]
	global_load_lds_dwordx4 v[232:233], off
	s_add_i32 m0, s31, 0xa000
	v_lshl_add_u64 v[232:233], v[230:231], 0, s[24:25]
	v_mfma_f32_32x32x16_bf16 v[98:113], v[194:197], v[206:209], v[98:113]
	v_mfma_f32_32x32x16_bf16 v[82:97], v[194:197], v[210:213], v[82:97]
	global_load_lds_dwordx4 v[232:233], off
	v_add3_u32 v170, s30, v136, v143
	v_add3_u32 v174, s30, v144, v146
	ds_read_b128 v[170:173], v170
	v_add3_u32 v178, s30, v145, v151
	ds_read_b128 v[174:177], v174
	v_add3_u32 v182, s30, v152, v156
	ds_read_b128 v[178:181], v178 offset:32768
	v_add3_u32 v186, s30, v155, v157
	ds_read_b128 v[182:185], v182 offset:32768
	v_add3_u32 v190, s30, v158, v168
	ds_read_b128 v[186:189], v186 offset:32768
	ds_read_b128 v[190:193], v190 offset:32768
	s_add_i32 m0, s31, 0xc000
	v_lshl_add_u64 v[232:233], v[230:231], 0, s[26:27]
	v_mfma_f32_32x32x16_bf16 v[66:81], v[194:197], v[226:229], v[66:81]
	v_mfma_f32_32x32x16_bf16 v[50:65], v[198:201], v[202:205], v[50:65]
	global_load_lds_dwordx4 v[232:233], off
	s_add_i32 m0, s31, 0xe000
	v_lshl_add_u64 v[232:233], v[230:231], 0, s[38:39]
	v_mfma_f32_32x32x16_bf16 v[34:49], v[198:201], v[206:209], v[34:49]
	v_mfma_f32_32x32x16_bf16 v[18:33], v[198:201], v[210:213], v[18:33]
	global_load_lds_dwordx4 v[232:233], off
	v_mfma_f32_32x32x16_bf16 v[2:17], v[198:201], v[226:229], v[2:17]
	s_branch .LBB0_173

; DI f32x16 mfma(bf16x8 a, bf16x8 b, f32x16 c) { return __builtin_amdgcn_mfma_f32_32x32x16_bf16(a, b, c, 0, 0, 0); }
; template <int BK> DI int swz(int row) { constexpr int CPR = BK / 8; return (row / (16 / CPR)) % CPR; }
; DI void wait_vm0() { asm volatile("s_waitcnt vmcnt(0)" ::: "memory"); }
;   DI void pre(int grow0, int gcol0, int lane, int w, char* lds) { xpass(0, grow0, gcol0, lane, w, lds); }
;     ...
;   for (int kt = 0; kt < nk; ++kt) {
;     char* cur = lds + (kt & 1) * STG; char* nxt = lds + ((kt + 1) & 1) * STG;
;     const bool more = kt + 1 < nk;
;     const bf16_t* An = Ag + (kt + 1) * BK; const bf16_t* Bn = Bg + (kt + 1) * BK;
;     if (!more) epi.pre(row0 + wm * 64, col0 + wn * (32 * NTW), lane, w, lds);
;     bf16x8 fa[2][2], fb[2][NTW];
; #pragma unroll
;     for (int mt = 0; mt < 2; ++mt) { int row = wm * 64 + mt * 32 + l31; fa[0][mt] = *(const bf16x8*)(cur + row * (BK * 2) + ((hh ^ swz<BK>(row)) << 4)); }
; #pragma unroll
;     for (int nt = 0; nt < NTW; ++nt) { int row = wn * (32 * NTW) + nt * 32 + l31; fb[0][nt] = *(const bf16x8*)(cur + ABYTES + row * (BK * 2) + ((hh ^ swz<BK>(row)) << 4)); }
; #pragma unroll
;     for (int kk = 0; kk < NKK; ++kk) {
;       if (kk + 1 < NKK) {
;         const int ch = (kk + 1) * 2 + hh;
; #pragma unroll
;         for (int mt = 0; mt < 2; ++mt) { int row = wm * 64 + mt * 32 + l31; fa[(kk + 1) & 1][mt] = *(const bf16x8*)(cur + row * (BK * 2) + ((ch ^ swz<BK>(row)) << 4)); }
; #pragma unroll
;         for (int nt = 0; nt < NTW; ++nt) { int row = wn * (32 * NTW) + nt * 32 + l31; fb[(kk + 1) & 1][nt] = *(const bf16x8*)(cur + ABYTES + row * (BK * 2) + ((ch ^ swz<BK>(row)) << 4)); }
;       }
;       if (more) {
; #pragma unroll
;         for (int q = 0; q < PPK; ++q) {
;           const int pi = kk * PPK + q;
;           if (pi < NPA) stage_piece<BM, BK>(An, lda, nxt, tid, pi, wv);
;           else if (pi < NP) stage_piece<BN, BK>(Bn, ldb, nxt + ABYTES, tid, pi - NPA, wv);
;         }
;       }
;       __builtin_amdgcn_s_setprio(1);
; #pragma unroll
;       for (int mt = 0; mt < 2; ++mt)
; #pragma unroll
;         for (int nt = 0; nt < NTW; ++nt) acc[mt][nt] = mfma(fa[kk & 1][mt], fb[kk & 1][nt], acc[mt][nt]);
;       __builtin_amdgcn_s_setprio(0);
;       __builtin_amdgcn_sched_barrier(0);
;     }
;     wait_vm0();
;     __syncthreads();
.LBB0_284:
	s_and_b32 s35, s7, 0x10000
	s_xor_b32 s100, s35, 0x10000
	v_add3_u32 v190, s100, v140, v161
	v_add3_u32 v194, s100, v142, v163
	ds_read_b128 v[190:193], v190
	v_add3_u32 v198, s100, v143, v159
	ds_read_b128 v[194:197], v194
	v_add3_u32 v202, s100, v152, v160
	ds_read_b128 v[198:201], v198 offset:32768
	v_add3_u32 v206, s100, v153, v157
	ds_read_b128 v[202:205], v202 offset:32768
	v_add3_u32 v210, s100, v156, v158
	ds_read_b128 v[206:209], v206 offset:32768
	ds_read_b128 v[210:213], v210 offset:32768
	s_waitcnt lgkmcnt(6)
	s_mov_b32 m0, s34
	v_lshl_add_u64 v[228:229], v[214:215], 0, s[28:29]
	v_mfma_f32_32x32x16_bf16 v[114:129], v[166:169], v[174:177], v[114:129]
	global_load_lds_dwordx4 v[228:229], off
	s_add_i32 m0, s34, 0x2000
	v_lshl_add_u64 v[228:229], v[214:215], 0, s[24:25]
	v_mfma_f32_32x32x16_bf16 v[98:113], v[166:169], v[178:181], v[98:113]
	v_mfma_f32_32x32x16_bf16 v[82:97], v[166:169], v[182:185], v[82:97]
	global_load_lds_dwordx4 v[228:229], off
	s_add_i32 m0, s34, 0x4000
	v_lshl_add_u64 v[228:229], v[214:215], 0, s[26:27]
	v_mfma_f32_32x32x16_bf16 v[66:81], v[166:169], v[186:189], v[66:81]
	v_mfma_f32_32x32x16_bf16 v[50:65], v[170:173], v[174:177], v[50:65]
	global_load_lds_dwordx4 v[228:229], off
	s_add_i32 m0, s34, 0x6000
	v_lshl_add_u64 v[228:229], v[214:215], 0, s[38:39]
	v_mfma_f32_32x32x16_bf16 v[34:49], v[170:173], v[178:181], v[34:49]
	v_mfma_f32_32x32x16_bf16 v[18:33], v[170:173], v[182:185], v[18:33]
	global_load_lds_dwordx4 v[228:229], off
	v_mfma_f32_32x32x16_bf16 v[2:17], v[170:173], v[186:189], v[2:17]
	v_add3_u32 v166, s100, v140, v149
	v_add3_u32 v170, s100, v142, v150
	ds_read_b128 v[166:169], v166
	v_add3_u32 v174, s100, v143, v147
	ds_read_b128 v[170:173], v170
	v_add3_u32 v178, s100, v152, v148
	ds_read_b128 v[174:177], v174 offset:32768
	v_add3_u32 v182, s100, v153, v145
	ds_read_b128 v[178:181], v178 offset:32768
	v_add3_u32 v186, s100, v156, v146
	ds_read_b128 v[182:185], v182 offset:32768
	ds_read_b128 v[186:189], v186 offset:32768
	s_waitcnt lgkmcnt(6)
	v_mfma_f32_32x32x16_bf16 v[114:129], v[190:193], v[198:201], v[114:129]
	v_mfma_f32_32x32x16_bf16 v[98:113], v[190:193], v[202:205], v[98:113]
	v_mfma_f32_32x32x16_bf16 v[82:97], v[190:193], v[206:209], v[82:97]
	v_mfma_f32_32x32x16_bf16 v[66:81], v[190:193], v[210:213], v[66:81]
	v_mfma_f32_32x32x16_bf16 v[50:65], v[194:197], v[198:201], v[50:65]
	v_mfma_f32_32x32x16_bf16 v[34:49], v[194:197], v[202:205], v[34:49]
	v_mfma_f32_32x32x16_bf16 v[18:33], v[194:197], v[206:209], v[18:33]
	v_mfma_f32_32x32x16_bf16 v[2:17], v[194:197], v[210:213], v[2:17]
	v_add3_u32 v190, s100, v140, v138
	v_add3_u32 v194, s100, v142, v139
	ds_read_b128 v[190:193], v190
	v_add3_u32 v198, s100, v143, v136
	ds_read_b128 v[194:197], v194
	v_add3_u32 v202, s100, v152, v137
	ds_read_b128 v[198:201], v198 offset:32768
	v_add3_u32 v206, s100, v153, v134
	ds_read_b128 v[202:205], v202 offset:32768
	v_add3_u32 v210, s100, v156, v135
	ds_read_b128 v[206:209], v206 offset:32768
	ds_read_b128 v[210:213], v210 offset:32768
	s_waitcnt lgkmcnt(6)
	v_mfma_f32_32x32x16_bf16 v[114:129], v[166:169], v[174:177], v[114:129]
	v_mfma_f32_32x32x16_bf16 v[98:113], v[166:169], v[178:181], v[98:113]
	v_mfma_f32_32x32x16_bf16 v[82:97], v[166:169], v[182:185], v[82:97]
	v_mfma_f32_32x32x16_bf16 v[66:81], v[166:169], v[186:189], v[66:81]
	v_mfma_f32_32x32x16_bf16 v[50:65], v[170:173], v[174:177], v[50:65]
	v_mfma_f32_32x32x16_bf16 v[34:49], v[170:173], v[178:181], v[34:49]
	v_mfma_f32_32x32x16_bf16 v[18:33], v[170:173], v[182:185], v[18:33]
	v_mfma_f32_32x32x16_bf16 v[2:17], v[170:173], v[186:189], v[2:17]
	s_add_u32 s30, s30, 0x80
	s_addc_u32 s31, s31, 0
	s_add_i32 s7, s7, 0x10000
	s_waitcnt vmcnt(0) lgkmcnt(0)
	s_barrier
	s_cmpk_eq_i32 s30, 0x780
	s_cbranch_scc1 .Lk284_exit
	s_add_i32 s34, s100, s3
	v_lshl_add_u64 v[214:215], v[130:131], 0, s[30:31]
	v_lshl_add_u64 v[226:227], v[132:133], 0, s[30:31]
	s_add_i32 m0, s34, 0x8000
	v_lshl_add_u64 v[228:229], v[226:227], 0, s[28:29]
	v_mfma_f32_32x32x16_bf16 v[114:129], v[190:193], v[198:201], v[114:129]
	global_load_lds_dwordx4 v[228:229], off
	s_add_i32 m0, s34, 0xa000
	v_lshl_add_u64 v[228:229], v[226:227], 0, s[24:25]
	v_mfma_f32_32x32x16_bf16 v[98:113], v[190:193], v[202:205], v[98:113]
	v_mfma_f32_32x32x16_bf16 v[82:97], v[190:193], v[206:209], v[82:97]
	global_load_lds_dwordx4 v[228:229], off
	v_add3_u32 v166, s35, v140, v141
	v_add3_u32 v170, s35, v142, v144
	ds_read_b128 v[166:169], v166
	v_add3_u32 v174, s35, v143, v151
	ds_read_b128 v[170:173], v170
	v_add3_u32 v178, s35, v152, v154
	ds_read_b128 v[174:177], v174 offset:32768
	v_add3_u32 v182, s35, v153, v155
	ds_read_b128 v[178:181], v178 offset:32768
	v_add3_u32 v186, s35, v156, v164
	ds_read_b128 v[182:185], v182 offset:32768
	ds_read_b128 v[186:189], v186 offset:32768
	s_add_i32 m0, s34, 0xc000
	v_lshl_add_u64 v[228:229], v[226:227], 0, s[26:27]
	v_mfma_f32_32x32x16_bf16 v[66:81], v[190:193], v[210:213], v[66:81]
	v_mfma_f32_32x32x16_bf16 v[50:65], v[194:197], v[198:201], v[50:65]
	global_load_lds_dwordx4 v[228:229], off
	s_add_i32 m0, s34, 0xe000
	v_lshl_add_u64 v[228:229], v[226:227], 0, s[38:39]
	v_mfma_f32_32x32x16_bf16 v[34:49], v[194:197], v[202:205], v[34:49]
	v_mfma_f32_32x32x16_bf16 v[18:33], v[194:197], v[206:209], v[18:33]
	global_load_lds_dwordx4 v[228:229], off
	v_mfma_f32_32x32x16_bf16 v[2:17], v[194:197], v[210:213], v[2:17]
	s_branch .LBB0_284

; DI f32x16 mfma(bf16x8 a, bf16x8 b, f32x16 c) { return __builtin_amdgcn_mfma_f32_32x32x16_bf16(a, b, c, 0, 0, 0); }
; template <int BK> DI int swz(int row) { constexpr int CPR = BK / 8; return (row / (16 / CPR)) % CPR; }
; DI void wait_vm0() { asm volatile("s_waitcnt vmcnt(0)" ::: "memory"); }
;   DI void pre(int grow0, int gcol0, int lane, int w, char* lds) { xpass(0, grow0, gcol0, lane, w, lds); }
;     ...
;   for (int kt = 0; kt < nk; ++kt) {
;     char* cur = lds + (kt & 1) * STG; char* nxt = lds + ((kt + 1) & 1) * STG;
;     const bool more = kt + 1 < nk;
;     const bf16_t* An = Ag + (kt + 1) * BK; const bf16_t* Bn = Bg + (kt + 1) * BK;
;     if (!more) epi.pre(row0 + wm * 64, col0 + wn * (32 * NTW), lane, w, lds);
;     bf16x8 fa[2][2], fb[2][NTW];
; #pragma unroll
;     for (int mt = 0; mt < 2; ++mt) { int row = wm * 64 + mt * 32 + l31; fa[0][mt] = *(const bf16x8*)(cur + row * (BK * 2) + ((hh ^ swz<BK>(row)) << 4)); }
; #pragma unroll
;     for (int nt = 0; nt < NTW; ++nt) { int row = wn * (32 * NTW) + nt * 32 + l31; fb[0][nt] = *(const bf16x8*)(cur + ABYTES + row * (BK * 2) + ((hh ^ swz<BK>(row)) << 4)); }
; #pragma unroll
;     for (int kk = 0; kk < NKK; ++kk) {
;       if (kk + 1 < NKK) {
;         const int ch = (kk + 1) * 2 + hh;
; #pragma unroll
;         for (int mt = 0; mt < 2; ++mt) { int row = wm * 64 + mt * 32 + l31; fa[(kk + 1) & 1][mt] = *(const bf16x8*)(cur + row * (BK * 2) + ((ch ^ swz<BK>(row)) << 4)); }
; #pragma unroll
;         for (int nt = 0; nt < NTW; ++nt) { int row = wn * (32 * NTW) + nt * 32 + l31; fb[(kk + 1) & 1][nt] = *(const bf16x8*)(cur + ABYTES + row * (BK * 2) + ((ch ^ swz<BK>(row)) << 4)); }
;       }
;       if (more) {
; #pragma unroll
;         for (int q = 0; q < PPK; ++q) {
;           const int pi = kk * PPK + q;
;           if (pi < NPA) stage_piece<BM, BK>(An, lda, nxt, tid, pi, wv);
;           else if (pi < NP) stage_piece<BN, BK>(Bn, ldb, nxt + ABYTES, tid, pi - NPA, wv);
;         }
;       }
;       __builtin_amdgcn_s_setprio(1);
; #pragma unroll
;       for (int mt = 0; mt < 2; ++mt)
; #pragma unroll
;         for (int nt = 0; nt < NTW; ++nt) acc[mt][nt] = mfma(fa[kk & 1][mt], fb[kk & 1][nt], acc[mt][nt]);
;       __builtin_amdgcn_s_setprio(0);
;       __builtin_amdgcn_sched_barrier(0);
;     }
;     wait_vm0();
;     __syncthreads();
.LBB0_292:
	s_and_b32 s30, s3, 0x10000
	s_xor_b32 s100, s30, 0x10000
	v_add3_u32 v194, s100, v136, v164
	v_add3_u32 v198, s100, v144, v166
	ds_read_b128 v[194:197], v194
	v_add3_u32 v202, s100, v145, v161
	ds_read_b128 v[198:201], v198
	v_add3_u32 v206, s100, v152, v163
	ds_read_b128 v[202:205], v202 offset:32768
	v_add3_u32 v210, s100, v155, v159
	ds_read_b128 v[206:209], v206 offset:32768
	v_add3_u32 v226, s100, v158, v160
	ds_read_b128 v[210:213], v210 offset:32768
	ds_read_b128 v[226:229], v226 offset:32768
	s_waitcnt lgkmcnt(6)
	s_mov_b32 m0, s31
	v_lshl_add_u64 v[232:233], v[214:215], 0, s[28:29]
	v_mfma_f32_32x32x16_bf16 v[114:129], v[170:173], v[178:181], v[114:129]
	global_load_lds_dwordx4 v[232:233], off
	s_add_i32 m0, s31, 0x2000
	v_lshl_add_u64 v[232:233], v[214:215], 0, s[36:37]
	v_mfma_f32_32x32x16_bf16 v[98:113], v[170:173], v[182:185], v[98:113]
	v_mfma_f32_32x32x16_bf16 v[82:97], v[170:173], v[186:189], v[82:97]
	global_load_lds_dwordx4 v[232:233], off
	s_add_i32 m0, s31, 0x4000
	v_lshl_add_u64 v[232:233], v[214:215], 0, s[40:41]
	v_mfma_f32_32x32x16_bf16 v[66:81], v[170:173], v[190:193], v[66:81]
	v_mfma_f32_32x32x16_bf16 v[50:65], v[174:177], v[178:181], v[50:65]
	global_load_lds_dwordx4 v[232:233], off
	s_add_i32 m0, s31, 0x6000
	v_lshl_add_u64 v[232:233], v[214:215], 0, s[42:43]
	v_mfma_f32_32x32x16_bf16 v[34:49], v[174:177], v[182:185], v[34:49]
	v_mfma_f32_32x32x16_bf16 v[18:33], v[174:177], v[186:189], v[18:33]
	global_load_lds_dwordx4 v[232:233], off
	v_mfma_f32_32x32x16_bf16 v[2:17], v[174:177], v[190:193], v[2:17]
	v_add3_u32 v170, s100, v136, v153
	v_add3_u32 v174, s100, v144, v154
	ds_read_b128 v[170:173], v170
	v_add3_u32 v178, s100, v145, v149
	ds_read_b128 v[174:177], v174
	v_add3_u32 v182, s100, v152, v150
	ds_read_b128 v[178:181], v178 offset:32768
	v_add3_u32 v186, s100, v155, v147
	ds_read_b128 v[182:185], v182 offset:32768
	v_add3_u32 v190, s100, v158, v148
	ds_read_b128 v[186:189], v186 offset:32768
	ds_read_b128 v[190:193], v190 offset:32768
	s_waitcnt lgkmcnt(6)
	v_mfma_f32_32x32x16_bf16 v[114:129], v[194:197], v[202:205], v[114:129]
	v_mfma_f32_32x32x16_bf16 v[98:113], v[194:197], v[206:209], v[98:113]
	v_mfma_f32_32x32x16_bf16 v[82:97], v[194:197], v[210:213], v[82:97]
	v_mfma_f32_32x32x16_bf16 v[66:81], v[194:197], v[226:229], v[66:81]
	v_mfma_f32_32x32x16_bf16 v[50:65], v[198:201], v[202:205], v[50:65]
	v_mfma_f32_32x32x16_bf16 v[34:49], v[198:201], v[206:209], v[34:49]
	v_mfma_f32_32x32x16_bf16 v[18:33], v[198:201], v[210:213], v[18:33]
	v_mfma_f32_32x32x16_bf16 v[2:17], v[198:201], v[226:229], v[2:17]
	v_add3_u32 v194, s100, v136, v141
	v_add3_u32 v198, s100, v144, v142
	ds_read_b128 v[194:197], v194
	v_add3_u32 v202, s100, v145, v139
	ds_read_b128 v[198:201], v198
	v_add3_u32 v206, s100, v152, v140
	ds_read_b128 v[202:205], v202 offset:32768
	v_add3_u32 v210, s100, v155, v137
	ds_read_b128 v[206:209], v206 offset:32768
	v_add3_u32 v226, s100, v158, v138
	ds_read_b128 v[210:213], v210 offset:32768
	ds_read_b128 v[226:229], v226 offset:32768
	s_waitcnt lgkmcnt(6)
	v_mfma_f32_32x32x16_bf16 v[114:129], v[170:173], v[178:181], v[114:129]
	v_mfma_f32_32x32x16_bf16 v[98:113], v[170:173], v[182:185], v[98:113]
	v_mfma_f32_32x32x16_bf16 v[82:97], v[170:173], v[186:189], v[82:97]
	v_mfma_f32_32x32x16_bf16 v[66:81], v[170:173], v[190:193], v[66:81]
	v_mfma_f32_32x32x16_bf16 v[50:65], v[174:177], v[178:181], v[50:65]
	v_mfma_f32_32x32x16_bf16 v[34:49], v[174:177], v[182:185], v[34:49]
	v_mfma_f32_32x32x16_bf16 v[18:33], v[174:177], v[186:189], v[18:33]
	v_mfma_f32_32x32x16_bf16 v[2:17], v[174:177], v[190:193], v[2:17]
	s_add_u32 s6, s6, 0x80
	s_addc_u32 s7, s7, 0
	s_add_i32 s3, s3, 0x10000
	s_waitcnt vmcnt(0) lgkmcnt(0)
	s_barrier
	s_cmpk_lg_i32 s6, 0x1580
	s_cbranch_scc0 .Lk292_exit
	s_add_i32 s31, s100, s2
	v_lshl_add_u64 v[214:215], v[132:133], 0, s[6:7]
	v_lshl_add_u64 v[230:231], v[130:131], 0, s[6:7]
	s_add_i32 m0, s31, 0x8000
	v_lshl_add_u64 v[232:233], v[230:231], 0, s[28:29]
	v_mfma_f32_32x32x16_bf16 v[114:129], v[194:197], v[202:205], v[114:129]
	global_load_lds_dwordx4 v[232:233], off
	s_add_i32 m0, s31, 0xa000
	v_lshl_add_u64 v[232:233], v[230:231], 0, s[36:37]
	v_mfma_f32_32x32x16_bf16 v[98:113], v[194:197], v[206:209], v[98:113]
	v_mfma_f32_32x32x16_bf16 v[82:97], v[194:197], v[210:213], v[82:97]
	global_load_lds_dwordx4 v[232:233], off
	v_add3_u32 v170, s30, v136, v143
	v_add3_u32 v174, s30, v144, v146
	ds_read_b128 v[170:173], v170
	v_add3_u32 v178, s30, v145, v151
	ds_read_b128 v[174:177], v174
	v_add3_u32 v182, s30, v152, v156
	ds_read_b128 v[178:181], v178 offset:32768
	v_add3_u32 v186, s30, v155, v157
	ds_read_b128 v[182:185], v182 offset:32768
	v_add3_u32 v190, s30, v158, v167
	ds_read_b128 v[186:189], v186 offset:32768
	ds_read_b128 v[190:193], v190 offset:32768
	s_add_i32 m0, s31, 0xc000
	v_lshl_add_u64 v[232:233], v[230:231], 0, s[40:41]
	v_mfma_f32_32x32x16_bf16 v[66:81], v[194:197], v[226:229], v[66:81]
	v_mfma_f32_32x32x16_bf16 v[50:65], v[198:201], v[202:205], v[50:65]
	global_load_lds_dwordx4 v[232:233], off
	s_add_i32 m0, s31, 0xe000
	v_lshl_add_u64 v[232:233], v[230:231], 0, s[42:43]
	v_mfma_f32_32x32x16_bf16 v[34:49], v[198:201], v[206:209], v[34:49]
	v_mfma_f32_32x32x16_bf16 v[18:33], v[198:201], v[210:213], v[18:33]
	global_load_lds_dwordx4 v[232:233], off
	v_mfma_f32_32x32x16_bf16 v[2:17], v[198:201], v[226:229], v[2:17]
	s_branch .LBB0_292

; DI f32x16 mfma(bf16x8 a, bf16x8 b, f32x16 c) { return __builtin_amdgcn_mfma_f32_32x32x16_bf16(a, b, c, 0, 0, 0); }
; template <int BK> DI int swz(int row) { constexpr int CPR = BK / 8; return (row / (16 / CPR)) % CPR; }
; DI void wait_vm0() { asm volatile("s_waitcnt vmcnt(0)" ::: "memory"); }
;   DI void pre(int grow0, int gcol0, int lane, int w, char* lds) { xpass(0, grow0, gcol0, lane, w, lds); }
;     ...
;   for (int kt = 0; kt < nk; ++kt) {
;     char* cur = lds + (kt & 1) * STG; char* nxt = lds + ((kt + 1) & 1) * STG;
;     const bool more = kt + 1 < nk;
;     const bf16_t* An = Ag + (kt + 1) * BK; const bf16_t* Bn = Bg + (kt + 1) * BK;
;     if (!more) epi.pre(row0 + wm * 64, col0 + wn * (32 * NTW), lane, w, lds);
;     bf16x8 fa[2][2], fb[2][NTW];
; #pragma unroll
;     for (int mt = 0; mt < 2; ++mt) { int row = wm * 64 + mt * 32 + l31; fa[0][mt] = *(const bf16x8*)(cur + row * (BK * 2) + ((hh ^ swz<BK>(row)) << 4)); }
; #pragma unroll
;     for (int nt = 0; nt < NTW; ++nt) { int row = wn * (32 * NTW) + nt * 32 + l31; fb[0][nt] = *(const bf16x8*)(cur + ABYTES + row * (BK * 2) + ((hh ^ swz<BK>(row)) << 4)); }
; #pragma unroll
;     for (int kk = 0; kk < NKK; ++kk) {
;       if (kk + 1 < NKK) {
;         const int ch = (kk + 1) * 2 + hh;
; #pragma unroll
;         for (int mt = 0; mt < 2; ++mt) { int row = wm * 64 + mt * 32 + l31; fa[(kk + 1) & 1][mt] = *(const bf16x8*)(cur + row * (BK * 2) + ((ch ^ swz<BK>(row)) << 4)); }
; #pragma unroll
;         for (int nt = 0; nt < NTW; ++nt) { int row = wn * (32 * NTW) + nt * 32 + l31; fb[(kk + 1) & 1][nt] = *(const bf16x8*)(cur + ABYTES + row * (BK * 2) + ((ch ^ swz<BK>(row)) << 4)); }
;       }
;       if (more) {
; #pragma unroll
;         for (int q = 0; q < PPK; ++q) {
;           const int pi = kk * PPK + q;
;           if (pi < NPA) stage_piece<BM, BK>(An, lda, nxt, tid, pi, wv);
;           else if (pi < NP) stage_piece<BN, BK>(Bn, ldb, nxt + ABYTES, tid, pi - NPA, wv);
;         }
;       }
;       __builtin_amdgcn_s_setprio(1);
; #pragma unroll
;       for (int mt = 0; mt < 2; ++mt)
; #pragma unroll
;         for (int nt = 0; nt < NTW; ++nt) acc[mt][nt] = mfma(fa[kk & 1][mt], fb[kk & 1][nt], acc[mt][nt]);
;       __builtin_amdgcn_s_setprio(0);
;       __builtin_amdgcn_sched_barrier(0);
;     }
;     wait_vm0();
;     __syncthreads();
.LBB0_382:
	s_and_b32 s42, s7, 0x10000
	s_xor_b32 s100, s42, 0x10000
	v_add3_u32 v190, s100, v140, v161
	v_add3_u32 v194, s100, v142, v163
	ds_read_b128 v[190:193], v190
	v_add3_u32 v198, s100, v143, v159
	ds_read_b128 v[194:197], v194
	v_add3_u32 v202, s100, v152, v160
	ds_read_b128 v[198:201], v198 offset:32768
	v_add3_u32 v206, s100, v153, v157
	ds_read_b128 v[202:205], v202 offset:32768
	v_add3_u32 v210, s100, v156, v158
	ds_read_b128 v[206:209], v206 offset:32768
	ds_read_b128 v[210:213], v210 offset:32768
	s_waitcnt lgkmcnt(6)
	s_mov_b32 m0, s37
	v_lshl_add_u64 v[228:229], v[214:215], 0, s[28:29]
	v_mfma_f32_32x32x16_bf16 v[114:129], v[166:169], v[174:177], v[114:129]
	global_load_lds_dwordx4 v[228:229], off
	s_add_i32 m0, s37, 0x2000
	v_lshl_add_u64 v[228:229], v[214:215], 0, s[24:25]
	v_mfma_f32_32x32x16_bf16 v[98:113], v[166:169], v[178:181], v[98:113]
	v_mfma_f32_32x32x16_bf16 v[82:97], v[166:169], v[182:185], v[82:97]
	global_load_lds_dwordx4 v[228:229], off
	s_add_i32 m0, s37, 0x4000
	v_lshl_add_u64 v[228:229], v[214:215], 0, s[26:27]
	v_mfma_f32_32x32x16_bf16 v[66:81], v[166:169], v[186:189], v[66:81]
	v_mfma_f32_32x32x16_bf16 v[50:65], v[170:173], v[174:177], v[50:65]
	global_load_lds_dwordx4 v[228:229], off
	s_add_i32 m0, s37, 0x6000
	v_lshl_add_u64 v[228:229], v[214:215], 0, s[38:39]
	v_mfma_f32_32x32x16_bf16 v[34:49], v[170:173], v[178:181], v[34:49]
	v_mfma_f32_32x32x16_bf16 v[18:33], v[170:173], v[182:185], v[18:33]
	global_load_lds_dwordx4 v[228:229], off
	v_mfma_f32_32x32x16_bf16 v[2:17], v[170:173], v[186:189], v[2:17]
	v_add3_u32 v166, s100, v140, v149
	v_add3_u32 v170, s100, v142, v150
	ds_read_b128 v[166:169], v166
	v_add3_u32 v174, s100, v143, v147
	ds_read_b128 v[170:173], v170
	v_add3_u32 v178, s100, v152, v148
	ds_read_b128 v[174:177], v174 offset:32768
	v_add3_u32 v182, s100, v153, v145
	ds_read_b128 v[178:181], v178 offset:32768
	v_add3_u32 v186, s100, v156, v146
	ds_read_b128 v[182:185], v182 offset:32768
	ds_read_b128 v[186:189], v186 offset:32768
	s_waitcnt lgkmcnt(6)
	v_mfma_f32_32x32x16_bf16 v[114:129], v[190:193], v[198:201], v[114:129]
	v_mfma_f32_32x32x16_bf16 v[98:113], v[190:193], v[202:205], v[98:113]
	v_mfma_f32_32x32x16_bf16 v[82:97], v[190:193], v[206:209], v[82:97]
	v_mfma_f32_32x32x16_bf16 v[66:81], v[190:193], v[210:213], v[66:81]
	v_mfma_f32_32x32x16_bf16 v[50:65], v[194:197], v[198:201], v[50:65]
	v_mfma_f32_32x32x16_bf16 v[34:49], v[194:197], v[202:205], v[34:49]
	v_mfma_f32_32x32x16_bf16 v[18:33], v[194:197], v[206:209], v[18:33]
	v_mfma_f32_32x32x16_bf16 v[2:17], v[194:197], v[210:213], v[2:17]
	v_add3_u32 v190, s100, v140, v138
	v_add3_u32 v194, s100, v142, v139
	ds_read_b128 v[190:193], v190
	v_add3_u32 v198, s100, v143, v136
	ds_read_b128 v[194:197], v194
	v_add3_u32 v202, s100, v152, v137
	ds_read_b128 v[198:201], v198 offset:32768
	v_add3_u32 v206, s100, v153, v134
	ds_read_b128 v[202:205], v202 offset:32768
	v_add3_u32 v210, s100, v156, v135
	ds_read_b128 v[206:209], v206 offset:32768
	ds_read_b128 v[210:213], v210 offset:32768
	s_waitcnt lgkmcnt(6)
	v_mfma_f32_32x32x16_bf16 v[114:129], v[166:169], v[174:177], v[114:129]
	v_mfma_f32_32x32x16_bf16 v[98:113], v[166:169], v[178:181], v[98:113]
	v_mfma_f32_32x32x16_bf16 v[82:97], v[166:169], v[182:185], v[82:97]
	v_mfma_f32_32x32x16_bf16 v[66:81], v[166:169], v[186:189], v[66:81]
	v_mfma_f32_32x32x16_bf16 v[50:65], v[170:173], v[174:177], v[50:65]
	v_mfma_f32_32x32x16_bf16 v[34:49], v[170:173], v[178:181], v[34:49]
	v_mfma_f32_32x32x16_bf16 v[18:33], v[170:173], v[182:185], v[18:33]
	v_mfma_f32_32x32x16_bf16 v[2:17], v[170:173], v[186:189], v[2:17]
	s_add_u32 s30, s30, 0x80
	s_addc_u32 s31, s31, 0
	s_add_i32 s7, s7, 0x10000
	s_waitcnt vmcnt(0) lgkmcnt(0)
	s_barrier
	s_cmpk_eq_i32 s30, 0x780
	s_cbranch_scc1 .Lk382_exit
	s_add_i32 s37, s100, s3
	v_lshl_add_u64 v[214:215], v[130:131], 0, s[30:31]
	v_lshl_add_u64 v[226:227], v[132:133], 0, s[30:31]
	s_add_i32 m0, s37, 0x8000
	v_lshl_add_u64 v[228:229], v[226:227], 0, s[28:29]
	v_mfma_f32_32x32x16_bf16 v[114:129], v[190:193], v[198:201], v[114:129]
	global_load_lds_dwordx4 v[228:229], off
	s_add_i32 m0, s37, 0xa000
	v_lshl_add_u64 v[228:229], v[226:227], 0, s[24:25]
	v_mfma_f32_32x32x16_bf16 v[98:113], v[190:193], v[202:205], v[98:113]
	v_mfma_f32_32x32x16_bf16 v[82:97], v[190:193], v[206:209], v[82:97]
	global_load_lds_dwordx4 v[228:229], off
	v_add3_u32 v166, s42, v140, v141
	v_add3_u32 v170, s42, v142, v144
	ds_read_b128 v[166:169], v166
	v_add3_u32 v174, s42, v143, v151
	ds_read_b128 v[170:173], v170
	v_add3_u32 v178, s42, v152, v154
	ds_read_b128 v[174:177], v174 offset:32768
	v_add3_u32 v182, s42, v153, v155
	ds_read_b128 v[178:181], v178 offset:32768
	v_add3_u32 v186, s42, v156, v164
	ds_read_b128 v[182:185], v182 offset:32768
	ds_read_b128 v[186:189], v186 offset:32768
	s_add_i32 m0, s37, 0xc000
	v_lshl_add_u64 v[228:229], v[226:227], 0, s[26:27]
	v_mfma_f32_32x32x16_bf16 v[66:81], v[190:193], v[210:213], v[66:81]
	v_mfma_f32_32x32x16_bf16 v[50:65], v[194:197], v[198:201], v[50:65]
	global_load_lds_dwordx4 v[228:229], off
	s_add_i32 m0, s37, 0xe000
	v_lshl_add_u64 v[228:229], v[226:227], 0, s[38:39]
	v_mfma_f32_32x32x16_bf16 v[34:49], v[194:197], v[202:205], v[34:49]
	v_mfma_f32_32x32x16_bf16 v[18:33], v[194:197], v[206:209], v[18:33]
	global_load_lds_dwordx4 v[228:229], off
	v_mfma_f32_32x32x16_bf16 v[2:17], v[194:197], v[210:213], v[2:17]
	s_branch .LBB0_382

; DI f32x16 mfma(bf16x8 a, bf16x8 b, f32x16 c) { return __builtin_amdgcn_mfma_f32_32x32x16_bf16(a, b, c, 0, 0, 0); }
;     ...
;   for (int kt = 0; kt < nk; ++kt) {
;     char* cur = lds + (kt & 1) * STG; char* nxt = lds + ((kt + 1) & 1) * STG;
;     const bool more = kt + 1 < nk;
;     const bf16_t* An = Ag + (kt + 1) * BK; const bf16_t* Bn = Bg + (kt + 1) * BK;
;     if (!more) epi.pre(row0 + wm * 64, col0 + wn * (32 * NTW), lane, w, lds);
;     bf16x8 fa[2][2], fb[2][NTW];
; #pragma unroll
;     for (int mt = 0; mt < 2; ++mt) { int row = wm * 64 + mt * 32 + l31; fa[0][mt] = *(const bf16x8*)(cur + row * (BK * 2) + ((hh ^ swz<BK>(row)) << 4)); }
; #pragma unroll
;     for (int nt = 0; nt < NTW; ++nt) { int row = wn * (32 * NTW) + nt * 32 + l31; fb[0][nt] = *(const bf16x8*)(cur + ABYTES + row * (BK * 2) + ((hh ^ swz<BK>(row)) << 4)); }
; #pragma unroll
;     for (int kk = 0; kk < NKK; ++kk) {
;       if (kk + 1 < NKK) {
;         const int ch = (kk + 1) * 2 + hh;
; #pragma unroll
;         for (int mt = 0; mt < 2; ++mt) { int row = wm * 64 + mt * 32 + l31; fa[(kk + 1) & 1][mt] = *(const bf16x8*)(cur + row * (BK * 2) + ((ch ^ swz<BK>(row)) << 4)); }
; #pragma unroll
;         for (int nt = 0; nt < NTW; ++nt) { int row = wn * (32 * NTW) + nt * 32 + l31; fb[(kk + 1) & 1][nt] = *(const bf16x8*)(cur + ABYTES + row * (BK * 2) + ((ch ^ swz<BK>(row)) << 4)); }
;       }
;       if (more) {
; #pragma unroll
;         for (int q = 0; q < PPK; ++q) {
;           const int pi = kk * PPK + q;
;           if (pi < NPA) stage_piece<BM, BK>(An, lda, nxt, tid, pi, wv);
;           else if (pi < NP) stage_piece<BN, BK>(Bn, ldb, nxt + ABYTES, tid, pi - NPA, wv);
;         }
;       }
;       __builtin_amdgcn_s_setprio(1);
; #pragma unroll
;       for (int mt = 0; mt < 2; ++mt)
; #pragma unroll
;         for (int nt = 0; nt < NTW; ++nt) acc[mt][nt] = mfma(fa[kk & 1][mt], fb[kk & 1][nt], acc[mt][nt]);
;       __builtin_amdgcn_s_setprio(0);
;       __builtin_amdgcn_sched_barrier(0);
;     }
;     wait_vm0();
;     __syncthreads();
; __global__ void __launch_bounds__(NT) fwd_megakernel(Params p) {
;     ...
;             for (int t = vb; t < 256; t += gridDim.x) {
;               const int x = t & 7, L = t >> 3; const int pm = 8 * x + (L & 7), pnh = L >> 3;
;               gemm_tile<4, 64, EpiSwiglu, 2>(p.Xb, D_, p.win[i * 2 + f], D_, D_, pm * 256, 5120 + pnh * 128, lds, e1);
;             }
.LBB0_388:
	s_bitcmp1_b32 s3, 0
	s_cselect_b32 s100, 0, 0xc000
	s_cselect_b32 s42, 0xc000, 0
	v_add3_u32 v106, s100, v70, v87
	v_add3_u32 v110, s100, v71, v88
	ds_read_b128 v[106:109], v106
	v_add3_u32 v114, s100, v77, v85
	ds_read_b128 v[110:113], v110
	v_add3_u32 v118, s100, v84, v86
	ds_read_b128 v[114:117], v114 offset:32768
	ds_read_b128 v[118:121], v118 offset:32768
	s_waitcnt lgkmcnt(4)
	s_mov_b32 m0, s37
	v_lshl_add_u64 v[126:127], v[122:123], 0, s[28:29]
	v_mfma_f32_32x32x16_bf16 v[50:65], v[90:93], v[98:101], v[50:65]
	global_load_lds_dwordx4 v[126:127], off
	s_add_i32 m0, s37, 0x2000
	v_lshl_add_u64 v[126:127], v[122:123], 0, s[24:25]
	v_mfma_f32_32x32x16_bf16 v[34:49], v[90:93], v[102:105], v[34:49]
	global_load_lds_dwordx4 v[126:127], off
	s_add_i32 m0, s37, 0x4000
	v_lshl_add_u64 v[126:127], v[122:123], 0, s[26:27]
	v_mfma_f32_32x32x16_bf16 v[18:33], v[94:97], v[98:101], v[18:33]
	global_load_lds_dwordx4 v[126:127], off
	v_mfma_f32_32x32x16_bf16 v[2:17], v[94:97], v[102:105], v[2:17]
	v_add3_u32 v90, s100, v70, v81
	v_add3_u32 v94, s100, v71, v82
	ds_read_b128 v[90:93], v90
	v_add3_u32 v98, s100, v77, v78
	ds_read_b128 v[94:97], v94
	v_add3_u32 v102, s100, v84, v79
	ds_read_b128 v[98:101], v98 offset:32768
	ds_read_b128 v[102:105], v102 offset:32768
	s_waitcnt lgkmcnt(4)
	v_mfma_f32_32x32x16_bf16 v[50:65], v[106:109], v[114:117], v[50:65]
	v_mfma_f32_32x32x16_bf16 v[34:49], v[106:109], v[118:121], v[34:49]
	v_mfma_f32_32x32x16_bf16 v[18:33], v[110:113], v[114:117], v[18:33]
	v_mfma_f32_32x32x16_bf16 v[2:17], v[110:113], v[118:121], v[2:17]
	v_add3_u32 v106, s100, v70, v74
	v_add3_u32 v110, s100, v71, v75
	ds_read_b128 v[106:109], v106
	v_add3_u32 v114, s100, v77, v72
	ds_read_b128 v[110:113], v110
	v_add3_u32 v118, s100, v84, v73
	ds_read_b128 v[114:117], v114 offset:32768
	ds_read_b128 v[118:121], v118 offset:32768
	s_waitcnt lgkmcnt(4)
	v_mfma_f32_32x32x16_bf16 v[50:65], v[90:93], v[98:101], v[50:65]
	v_mfma_f32_32x32x16_bf16 v[34:49], v[90:93], v[102:105], v[34:49]
	v_mfma_f32_32x32x16_bf16 v[18:33], v[94:97], v[98:101], v[18:33]
	v_mfma_f32_32x32x16_bf16 v[2:17], v[94:97], v[102:105], v[2:17]
	s_add_u32 s30, s30, 0x80
	s_addc_u32 s31, s31, 0
	s_add_i32 s3, s3, 1
	s_waitcnt vmcnt(0) lgkmcnt(0)
	s_barrier
	s_cmpk_lg_i32 s30, 0x780
	s_cbranch_scc0 .Lk388_exit
	s_add_i32 s37, s7, s100
	v_lshl_add_u64 v[122:123], v[66:67], 0, s[30:31]
	v_lshl_add_u64 v[124:125], v[68:69], 0, s[30:31]
	s_add_i32 m0, s37, 0x6000
	v_lshl_add_u64 v[126:127], v[122:123], 0, s[38:39]
	v_mfma_f32_32x32x16_bf16 v[50:65], v[106:109], v[114:117], v[50:65]
	global_load_lds_dwordx4 v[126:127], off
	s_add_i32 m0, s37, 0x8000
	v_lshl_add_u64 v[126:127], v[124:125], 0, s[28:29]
	v_mfma_f32_32x32x16_bf16 v[34:49], v[106:109], v[118:121], v[34:49]
	global_load_lds_dwordx4 v[126:127], off
	v_add3_u32 v90, s42, v70, v76
	v_add3_u32 v94, s42, v71, v80
	ds_read_b128 v[90:93], v90
	v_add3_u32 v98, s42, v77, v83
	ds_read_b128 v[94:97], v94
	v_add3_u32 v102, s42, v84, v89
	ds_read_b128 v[98:101], v98 offset:32768
	ds_read_b128 v[102:105], v102 offset:32768
	s_add_i32 m0, s37, 0xa000
	v_lshl_add_u64 v[126:127], v[124:125], 0, s[24:25]
	v_mfma_f32_32x32x16_bf16 v[18:33], v[110:113], v[114:117], v[18:33]
	global_load_lds_dwordx4 v[126:127], off
	v_mfma_f32_32x32x16_bf16 v[2:17], v[110:113], v[118:121], v[2:17]
	s_branch .LBB0_388

; DI f32x16 mfma(bf16x8 a, bf16x8 b, f32x16 c) { return __builtin_amdgcn_mfma_f32_32x32x16_bf16(a, b, c, 0, 0, 0); }
; template <int BK> DI int swz(int row) { constexpr int CPR = BK / 8; return (row / (16 / CPR)) % CPR; }
; DI void wait_vm0() { asm volatile("s_waitcnt vmcnt(0)" ::: "memory"); }
;   DI void pre(int grow0, int gcol0, int lane, int w, char* lds) { xpass(0, grow0, gcol0, lane, w, lds); }
;     ...
;   for (int kt = 0; kt < nk; ++kt) {
;     char* cur = lds + (kt & 1) * STG; char* nxt = lds + ((kt + 1) & 1) * STG;
;     const bool more = kt + 1 < nk;
;     const bf16_t* An = Ag + (kt + 1) * BK; const bf16_t* Bn = Bg + (kt + 1) * BK;
;     if (!more) epi.pre(row0 + wm * 64, col0 + wn * (32 * NTW), lane, w, lds);
;     bf16x8 fa[2][2], fb[2][NTW];
; #pragma unroll
;     for (int mt = 0; mt < 2; ++mt) { int row = wm * 64 + mt * 32 + l31; fa[0][mt] = *(const bf16x8*)(cur + row * (BK * 2) + ((hh ^ swz<BK>(row)) << 4)); }
; #pragma unroll
;     for (int nt = 0; nt < NTW; ++nt) { int row = wn * (32 * NTW) + nt * 32 + l31; fb[0][nt] = *(const bf16x8*)(cur + ABYTES + row * (BK * 2) + ((hh ^ swz<BK>(row)) << 4)); }
; #pragma unroll
;     for (int kk = 0; kk < NKK; ++kk) {
;       if (kk + 1 < NKK) {
;         const int ch = (kk + 1) * 2 + hh;
; #pragma unroll
;         for (int mt = 0; mt < 2; ++mt) { int row = wm * 64 + mt * 32 + l31; fa[(kk + 1) & 1][mt] = *(const bf16x8*)(cur + row * (BK * 2) + ((ch ^ swz<BK>(row)) << 4)); }
; #pragma unroll
;         for (int nt = 0; nt < NTW; ++nt) { int row = wn * (32 * NTW) + nt * 32 + l31; fb[(kk + 1) & 1][nt] = *(const bf16x8*)(cur + ABYTES + row * (BK * 2) + ((ch ^ swz<BK>(row)) << 4)); }
;       }
;       if (more) {
; #pragma unroll
;         for (int q = 0; q < PPK; ++q) {
;           const int pi = kk * PPK + q;
;           if (pi < NPA) stage_piece<BM, BK>(An, lda, nxt, tid, pi, wv);
;           else if (pi < NP) stage_piece<BN, BK>(Bn, ldb, nxt + ABYTES, tid, pi - NPA, wv);
;         }
;       }
;       __builtin_amdgcn_s_setprio(1);
; #pragma unroll
;       for (int mt = 0; mt < 2; ++mt)
; #pragma unroll
;         for (int nt = 0; nt < NTW; ++nt) acc[mt][nt] = mfma(fa[kk & 1][mt], fb[kk & 1][nt], acc[mt][nt]);
;       __builtin_amdgcn_s_setprio(0);
;       __builtin_amdgcn_sched_barrier(0);
;     }
;     wait_vm0();
;     __syncthreads();
.LBB0_439:
	s_and_b32 s40, s7, 0x10000
	s_xor_b32 s100, s40, 0x10000
	v_add3_u32 v190, s100, v140, v161
	v_add3_u32 v194, s100, v142, v163
	ds_read_b128 v[190:193], v190
	v_add3_u32 v198, s100, v143, v159
	ds_read_b128 v[194:197], v194
	v_add3_u32 v202, s100, v152, v160
	ds_read_b128 v[198:201], v198 offset:32768
	v_add3_u32 v206, s100, v153, v157
	ds_read_b128 v[202:205], v202 offset:32768
	v_add3_u32 v210, s100, v156, v158
	ds_read_b128 v[206:209], v206 offset:32768
	ds_read_b128 v[210:213], v210 offset:32768
	s_waitcnt lgkmcnt(6)
	s_mov_b32 m0, s37
	v_lshl_add_u64 v[228:229], v[214:215], 0, s[28:29]
	v_mfma_f32_32x32x16_bf16 v[114:129], v[166:169], v[174:177], v[114:129]
	global_load_lds_dwordx4 v[228:229], off
	s_add_i32 m0, s37, 0x2000
	v_lshl_add_u64 v[228:229], v[214:215], 0, s[24:25]
	v_mfma_f32_32x32x16_bf16 v[98:113], v[166:169], v[178:181], v[98:113]
	v_mfma_f32_32x32x16_bf16 v[50:65], v[166:169], v[182:185], v[50:65]
	global_load_lds_dwordx4 v[228:229], off
	s_add_i32 m0, s37, 0x4000
	v_lshl_add_u64 v[228:229], v[214:215], 0, s[26:27]
	v_mfma_f32_32x32x16_bf16 v[34:49], v[166:169], v[186:189], v[34:49]
	v_mfma_f32_32x32x16_bf16 v[82:97], v[170:173], v[174:177], v[82:97]
	global_load_lds_dwordx4 v[228:229], off
	s_add_i32 m0, s37, 0x6000
	v_lshl_add_u64 v[228:229], v[214:215], 0, s[38:39]
	v_mfma_f32_32x32x16_bf16 v[66:81], v[170:173], v[178:181], v[66:81]
	v_mfma_f32_32x32x16_bf16 v[18:33], v[170:173], v[182:185], v[18:33]
	global_load_lds_dwordx4 v[228:229], off
	v_mfma_f32_32x32x16_bf16 v[2:17], v[170:173], v[186:189], v[2:17]
	v_add3_u32 v166, s100, v140, v149
	v_add3_u32 v170, s100, v142, v150
	ds_read_b128 v[166:169], v166
	v_add3_u32 v174, s100, v143, v147
	ds_read_b128 v[170:173], v170
	v_add3_u32 v178, s100, v152, v148
	ds_read_b128 v[174:177], v174 offset:32768
	v_add3_u32 v182, s100, v153, v145
	ds_read_b128 v[178:181], v178 offset:32768
	v_add3_u32 v186, s100, v156, v146
	ds_read_b128 v[182:185], v182 offset:32768
	ds_read_b128 v[186:189], v186 offset:32768
	s_waitcnt lgkmcnt(6)
	v_mfma_f32_32x32x16_bf16 v[114:129], v[190:193], v[198:201], v[114:129]
	v_mfma_f32_32x32x16_bf16 v[98:113], v[190:193], v[202:205], v[98:113]
	v_mfma_f32_32x32x16_bf16 v[50:65], v[190:193], v[206:209], v[50:65]
	v_mfma_f32_32x32x16_bf16 v[34:49], v[190:193], v[210:213], v[34:49]
	v_mfma_f32_32x32x16_bf16 v[82:97], v[194:197], v[198:201], v[82:97]
	v_mfma_f32_32x32x16_bf16 v[66:81], v[194:197], v[202:205], v[66:81]
	v_mfma_f32_32x32x16_bf16 v[18:33], v[194:197], v[206:209], v[18:33]
	v_mfma_f32_32x32x16_bf16 v[2:17], v[194:197], v[210:213], v[2:17]
	v_add3_u32 v190, s100, v140, v138
	v_add3_u32 v194, s100, v142, v139
	ds_read_b128 v[190:193], v190
	v_add3_u32 v198, s100, v143, v136
	ds_read_b128 v[194:197], v194
	v_add3_u32 v202, s100, v152, v137
	ds_read_b128 v[198:201], v198 offset:32768
	v_add3_u32 v206, s100, v153, v134
	ds_read_b128 v[202:205], v202 offset:32768
	v_add3_u32 v210, s100, v156, v135
	ds_read_b128 v[206:209], v206 offset:32768
	ds_read_b128 v[210:213], v210 offset:32768
	s_waitcnt lgkmcnt(6)
	v_mfma_f32_32x32x16_bf16 v[114:129], v[166:169], v[174:177], v[114:129]
	v_mfma_f32_32x32x16_bf16 v[98:113], v[166:169], v[178:181], v[98:113]
	v_mfma_f32_32x32x16_bf16 v[50:65], v[166:169], v[182:185], v[50:65]
	v_mfma_f32_32x32x16_bf16 v[34:49], v[166:169], v[186:189], v[34:49]
	v_mfma_f32_32x32x16_bf16 v[82:97], v[170:173], v[174:177], v[82:97]
	v_mfma_f32_32x32x16_bf16 v[66:81], v[170:173], v[178:181], v[66:81]
	v_mfma_f32_32x32x16_bf16 v[18:33], v[170:173], v[182:185], v[18:33]
	v_mfma_f32_32x32x16_bf16 v[2:17], v[170:173], v[186:189], v[2:17]
	s_add_u32 s30, s30, 0x80
	s_addc_u32 s31, s31, 0
	s_add_i32 s7, s7, 0x10000
	s_waitcnt vmcnt(0) lgkmcnt(0)
	s_barrier
	s_cmpk_eq_i32 s30, 0x780
	s_cbranch_scc1 .Lk439_exit
	s_add_i32 s37, s100, s3
	v_lshl_add_u64 v[214:215], v[130:131], 0, s[30:31]
	v_lshl_add_u64 v[226:227], v[132:133], 0, s[30:31]
	s_add_i32 m0, s37, 0x8000
	v_lshl_add_u64 v[228:229], v[226:227], 0, s[28:29]
	v_mfma_f32_32x32x16_bf16 v[114:129], v[190:193], v[198:201], v[114:129]
	global_load_lds_dwordx4 v[228:229], off
	s_add_i32 m0, s37, 0xa000
	v_lshl_add_u64 v[228:229], v[226:227], 0, s[24:25]
	v_mfma_f32_32x32x16_bf16 v[98:113], v[190:193], v[202:205], v[98:113]
	v_mfma_f32_32x32x16_bf16 v[50:65], v[190:193], v[206:209], v[50:65]
	global_load_lds_dwordx4 v[228:229], off
	v_add3_u32 v166, s40, v140, v141
	v_add3_u32 v170, s40, v142, v144
	ds_read_b128 v[166:169], v166
	v_add3_u32 v174, s40, v143, v151
	ds_read_b128 v[170:173], v170
	v_add3_u32 v178, s40, v152, v154
	ds_read_b128 v[174:177], v174 offset:32768
	v_add3_u32 v182, s40, v153, v155
	ds_read_b128 v[178:181], v178 offset:32768
	v_add3_u32 v186, s40, v156, v164
	ds_read_b128 v[182:185], v182 offset:32768
	ds_read_b128 v[186:189], v186 offset:32768
	s_add_i32 m0, s37, 0xc000
	v_lshl_add_u64 v[228:229], v[226:227], 0, s[26:27]
	v_mfma_f32_32x32x16_bf16 v[34:49], v[190:193], v[210:213], v[34:49]
	v_mfma_f32_32x32x16_bf16 v[82:97], v[194:197], v[198:201], v[82:97]
	global_load_lds_dwordx4 v[228:229], off
	s_add_i32 m0, s37, 0xe000
	v_lshl_add_u64 v[228:229], v[226:227], 0, s[38:39]
	v_mfma_f32_32x32x16_bf16 v[66:81], v[194:197], v[202:205], v[66:81]
	v_mfma_f32_32x32x16_bf16 v[18:33], v[194:197], v[206:209], v[18:33]
	global_load_lds_dwordx4 v[228:229], off
	v_mfma_f32_32x32x16_bf16 v[2:17], v[194:197], v[210:213], v[2:17]
	s_branch .LBB0_439

; DI f32x16 mfma(bf16x8 a, bf16x8 b, f32x16 c) { return __builtin_amdgcn_mfma_f32_32x32x16_bf16(a, b, c, 0, 0, 0); }
; template <int BK> DI int swz(int row) { constexpr int CPR = BK / 8; return (row / (16 / CPR)) % CPR; }
; DI void wait_vm0() { asm volatile("s_waitcnt vmcnt(0)" ::: "memory"); }
;   DI void pre(int grow0, int gcol0, int lane, int w, char* lds) { xpass(0, grow0, gcol0, lane, w, lds); }
;     ...
;   for (int kt = 0; kt < nk; ++kt) {
;     char* cur = lds + (kt & 1) * STG; char* nxt = lds + ((kt + 1) & 1) * STG;
;     const bool more = kt + 1 < nk;
;     const bf16_t* An = Ag + (kt + 1) * BK; const bf16_t* Bn = Bg + (kt + 1) * BK;
;     if (!more) epi.pre(row0 + wm * 64, col0 + wn * (32 * NTW), lane, w, lds);
;     bf16x8 fa[2][2], fb[2][NTW];
; #pragma unroll
;     for (int mt = 0; mt < 2; ++mt) { int row = wm * 64 + mt * 32 + l31; fa[0][mt] = *(const bf16x8*)(cur + row * (BK * 2) + ((hh ^ swz<BK>(row)) << 4)); }
; #pragma unroll
;     for (int nt = 0; nt < NTW; ++nt) { int row = wn * (32 * NTW) + nt * 32 + l31; fb[0][nt] = *(const bf16x8*)(cur + ABYTES + row * (BK * 2) + ((hh ^ swz<BK>(row)) << 4)); }
; #pragma unroll
;     for (int kk = 0; kk < NKK; ++kk) {
;       if (kk + 1 < NKK) {
;         const int ch = (kk + 1) * 2 + hh;
; #pragma unroll
;         for (int mt = 0; mt < 2; ++mt) { int row = wm * 64 + mt * 32 + l31; fa[(kk + 1) & 1][mt] = *(const bf16x8*)(cur + row * (BK * 2) + ((ch ^ swz<BK>(row)) << 4)); }
; #pragma unroll
;         for (int nt = 0; nt < NTW; ++nt) { int row = wn * (32 * NTW) + nt * 32 + l31; fb[(kk + 1) & 1][nt] = *(const bf16x8*)(cur + ABYTES + row * (BK * 2) + ((ch ^ swz<BK>(row)) << 4)); }
;       }
;       if (more) {
; #pragma unroll
;         for (int q = 0; q < PPK; ++q) {
;           const int pi = kk * PPK + q;
;           if (pi < NPA) stage_piece<BM, BK>(An, lda, nxt, tid, pi, wv);
;           else if (pi < NP) stage_piece<BN, BK>(Bn, ldb, nxt + ABYTES, tid, pi - NPA, wv);
;         }
;       }
;       __builtin_amdgcn_s_setprio(1);
; #pragma unroll
;       for (int mt = 0; mt < 2; ++mt)
; #pragma unroll
;         for (int nt = 0; nt < NTW; ++nt) acc[mt][nt] = mfma(fa[kk & 1][mt], fb[kk & 1][nt], acc[mt][nt]);
;       __builtin_amdgcn_s_setprio(0);
;       __builtin_amdgcn_sched_barrier(0);
;     }
;     wait_vm0();
;     __syncthreads();
.LBB0_532:
	s_and_b32 s7, s3, 0x10000
	s_xor_b32 s100, s7, 0x10000
	v_add3_u32 v194, s100, v136, v166
	v_add3_u32 v198, s100, v144, v167
	ds_read_b128 v[194:197], v194
	v_add3_u32 v202, s100, v145, v163
	ds_read_b128 v[198:201], v198
	v_add3_u32 v206, s100, v150, v164
	ds_read_b128 v[202:205], v202 offset:32768
	v_add3_u32 v210, s100, v156, v159
	ds_read_b128 v[206:209], v206 offset:32768
	v_add3_u32 v226, s100, v158, v160
	ds_read_b128 v[210:213], v210 offset:32768
	ds_read_b128 v[226:229], v226 offset:32768
	s_waitcnt lgkmcnt(6)
	s_mov_b32 m0, s101
	v_mov_b64_e32 v[232:233], v[230:231]
	v_mfma_f32_32x32x16_bf16 v[114:129], v[170:173], v[178:181], v[114:129]
	global_load_lds_dwordx4 v[232:233], off
	v_mfma_f32_32x32x16_bf16 v[98:113], v[170:173], v[182:185], v[98:113]
	s_add_i32 m0, s101, 0x2000
	v_lshl_add_u64 v[232:233], v[230:231], 0, s[36:37]
	v_mfma_f32_32x32x16_bf16 v[82:97], v[170:173], v[186:189], v[82:97]
	global_load_lds_dwordx4 v[232:233], off
	v_mfma_f32_32x32x16_bf16 v[66:81], v[170:173], v[190:193], v[66:81]
	s_add_i32 m0, s101, 0x4000
	v_lshl_add_u64 v[232:233], v[230:231], 0, s[40:41]
	v_mfma_f32_32x32x16_bf16 v[50:65], v[174:177], v[178:181], v[50:65]
	global_load_lds_dwordx4 v[232:233], off
	v_mfma_f32_32x32x16_bf16 v[34:49], v[174:177], v[182:185], v[34:49]
	s_add_i32 m0, s101, 0x6000
	v_lshl_add_u64 v[232:233], v[230:231], 0, s[34:35]
	v_mfma_f32_32x32x16_bf16 v[18:33], v[174:177], v[186:189], v[18:33]
	global_load_lds_dwordx4 v[232:233], off
	v_mfma_f32_32x32x16_bf16 v[2:17], v[174:177], v[190:193], v[2:17]
	v_add3_u32 v170, s100, v136, v153
	v_add3_u32 v174, s100, v144, v154
	ds_read_b128 v[170:173], v170
	v_add3_u32 v178, s100, v145, v151
	ds_read_b128 v[174:177], v174
	v_add3_u32 v182, s100, v150, v152
	ds_read_b128 v[178:181], v178 offset:32768
	v_add3_u32 v186, s100, v156, v147
	ds_read_b128 v[182:185], v182 offset:32768
	v_add3_u32 v190, s100, v158, v148
	ds_read_b128 v[186:189], v186 offset:32768
	ds_read_b128 v[190:193], v190 offset:32768
	s_waitcnt lgkmcnt(6)
	v_mfma_f32_32x32x16_bf16 v[114:129], v[194:197], v[202:205], v[114:129]
	v_mfma_f32_32x32x16_bf16 v[98:113], v[194:197], v[206:209], v[98:113]
	v_mfma_f32_32x32x16_bf16 v[82:97], v[194:197], v[210:213], v[82:97]
	v_mfma_f32_32x32x16_bf16 v[66:81], v[194:197], v[226:229], v[66:81]
	v_mfma_f32_32x32x16_bf16 v[50:65], v[198:201], v[202:205], v[50:65]
	v_mfma_f32_32x32x16_bf16 v[34:49], v[198:201], v[206:209], v[34:49]
	v_mfma_f32_32x32x16_bf16 v[18:33], v[198:201], v[210:213], v[18:33]
	v_mfma_f32_32x32x16_bf16 v[2:17], v[198:201], v[226:229], v[2:17]
	v_add3_u32 v194, s100, v136, v141
	v_add3_u32 v198, s100, v144, v142
	ds_read_b128 v[194:197], v194
	v_add3_u32 v202, s100, v145, v139
	ds_read_b128 v[198:201], v198
	v_add3_u32 v206, s100, v150, v140
	ds_read_b128 v[202:205], v202 offset:32768
	v_add3_u32 v210, s100, v156, v137
	ds_read_b128 v[206:209], v206 offset:32768
	v_add3_u32 v226, s100, v158, v138
	ds_read_b128 v[210:213], v210 offset:32768
	ds_read_b128 v[226:229], v226 offset:32768
	s_waitcnt lgkmcnt(6)
	v_mfma_f32_32x32x16_bf16 v[114:129], v[170:173], v[178:181], v[114:129]
	v_mfma_f32_32x32x16_bf16 v[98:113], v[170:173], v[182:185], v[98:113]
	v_mfma_f32_32x32x16_bf16 v[82:97], v[170:173], v[186:189], v[82:97]
	v_mfma_f32_32x32x16_bf16 v[66:81], v[170:173], v[190:193], v[66:81]
	v_mfma_f32_32x32x16_bf16 v[50:65], v[174:177], v[178:181], v[50:65]
	v_mfma_f32_32x32x16_bf16 v[34:49], v[174:177], v[182:185], v[34:49]
	v_mfma_f32_32x32x16_bf16 v[18:33], v[174:177], v[186:189], v[18:33]
	v_mfma_f32_32x32x16_bf16 v[2:17], v[174:177], v[190:193], v[2:17]
	s_add_i32 s6, s6, -1
	s_add_i32 s92, s92, 64
	s_add_i32 s3, s3, 0x10000
	s_waitcnt vmcnt(0) lgkmcnt(0)
	s_barrier
	s_cmp_lg_u32 s6, 0
	s_cbranch_scc0 .Lk532_exit
	s_add_i32 s101, s100, s2
	s_lshl_b64 s[30:31], s[92:93], 1
	v_lshl_add_u64 v[230:231], v[130:131], 0, s[30:31]
	v_lshl_add_u64 v[214:215], v[132:133], 0, s[30:31]
	s_add_i32 m0, s101, 0x8000
	v_mov_b64_e32 v[232:233], v[214:215]
	v_mfma_f32_32x32x16_bf16 v[114:129], v[194:197], v[202:205], v[114:129]
	global_load_lds_dwordx4 v[232:233], off
	v_mfma_f32_32x32x16_bf16 v[98:113], v[194:197], v[206:209], v[98:113]
	s_add_i32 m0, s101, 0xa000
	v_lshl_add_u64 v[232:233], v[214:215], 0, s[36:37]
	v_mfma_f32_32x32x16_bf16 v[82:97], v[194:197], v[210:213], v[82:97]
	global_load_lds_dwordx4 v[232:233], off
	v_add3_u32 v170, s7, v136, v143
	v_add3_u32 v174, s7, v144, v146
	ds_read_b128 v[170:173], v170
	v_add3_u32 v178, s7, v145, v149
	ds_read_b128 v[174:177], v174
	v_add3_u32 v182, s7, v150, v155
	ds_read_b128 v[178:181], v178 offset:32768
	v_add3_u32 v186, s7, v156, v157
	ds_read_b128 v[182:185], v182 offset:32768
	v_add3_u32 v190, s7, v158, v168
	ds_read_b128 v[186:189], v186 offset:32768
	ds_read_b128 v[190:193], v190 offset:32768
	v_mfma_f32_32x32x16_bf16 v[66:81], v[194:197], v[226:229], v[66:81]
	s_add_i32 m0, s101, 0xc000
	v_lshl_add_u64 v[232:233], v[214:215], 0, s[40:41]
	v_mfma_f32_32x32x16_bf16 v[50:65], v[198:201], v[202:205], v[50:65]
	global_load_lds_dwordx4 v[232:233], off
	v_mfma_f32_32x32x16_bf16 v[34:49], v[198:201], v[206:209], v[34:49]
	s_add_i32 m0, s101, 0xe000
	v_lshl_add_u64 v[232:233], v[214:215], 0, s[34:35]
	v_mfma_f32_32x32x16_bf16 v[18:33], v[198:201], v[210:213], v[18:33]
	global_load_lds_dwordx4 v[232:233], off
	v_mfma_f32_32x32x16_bf16 v[2:17], v[198:201], v[226:229], v[2:17]
	s_branch .LBB0_532

; DI f32x16 mfma(bf16x8 a, bf16x8 b, f32x16 c) { return __builtin_amdgcn_mfma_f32_32x32x16_bf16(a, b, c, 0, 0, 0); }
; template <int BK> DI int swz(int row) { constexpr int CPR = BK / 8; return (row / (16 / CPR)) % CPR; }
; DI void wait_vm0() { asm volatile("s_waitcnt vmcnt(0)" ::: "memory"); }
;   DI void pre(int grow0, int gcol0, int lane, int w, char* lds) { xpass(0, grow0, gcol0, lane, w, lds); }
;     ...
;   for (int kt = 0; kt < nk; ++kt) {
;     char* cur = lds + (kt & 1) * STG; char* nxt = lds + ((kt + 1) & 1) * STG;
;     const bool more = kt + 1 < nk;
;     const bf16_t* An = Ag + (kt + 1) * BK; const bf16_t* Bn = Bg + (kt + 1) * BK;
;     if (!more) epi.pre(row0 + wm * 64, col0 + wn * (32 * NTW), lane, w, lds);
;     bf16x8 fa[2][2], fb[2][NTW];
; #pragma unroll
;     for (int mt = 0; mt < 2; ++mt) { int row = wm * 64 + mt * 32 + l31; fa[0][mt] = *(const bf16x8*)(cur + row * (BK * 2) + ((hh ^ swz<BK>(row)) << 4)); }
; #pragma unroll
;     for (int nt = 0; nt < NTW; ++nt) { int row = wn * (32 * NTW) + nt * 32 + l31; fb[0][nt] = *(const bf16x8*)(cur + ABYTES + row * (BK * 2) + ((hh ^ swz<BK>(row)) << 4)); }
; #pragma unroll
;     for (int kk = 0; kk < NKK; ++kk) {
;       if (kk + 1 < NKK) {
;         const int ch = (kk + 1) * 2 + hh;
; #pragma unroll
;         for (int mt = 0; mt < 2; ++mt) { int row = wm * 64 + mt * 32 + l31; fa[(kk + 1) & 1][mt] = *(const bf16x8*)(cur + row * (BK * 2) + ((ch ^ swz<BK>(row)) << 4)); }
; #pragma unroll
;         for (int nt = 0; nt < NTW; ++nt) { int row = wn * (32 * NTW) + nt * 32 + l31; fb[(kk + 1) & 1][nt] = *(const bf16x8*)(cur + ABYTES + row * (BK * 2) + ((ch ^ swz<BK>(row)) << 4)); }
;       }
;       if (more) {
; #pragma unroll
;         for (int q = 0; q < PPK; ++q) {
;           const int pi = kk * PPK + q;
;           if (pi < NPA) stage_piece<BM, BK>(An, lda, nxt, tid, pi, wv);
;           else if (pi < NP) stage_piece<BN, BK>(Bn, ldb, nxt + ABYTES, tid, pi - NPA, wv);
;         }
;       }
;       __builtin_amdgcn_s_setprio(1);
; #pragma unroll
;       for (int mt = 0; mt < 2; ++mt)
; #pragma unroll
;         for (int nt = 0; nt < NTW; ++nt) acc[mt][nt] = mfma(fa[kk & 1][mt], fb[kk & 1][nt], acc[mt][nt]);
;       __builtin_amdgcn_s_setprio(0);
;       __builtin_amdgcn_sched_barrier(0);
;     }
;     wait_vm0();
;     __syncthreads();
.LBB0_627:
	s_and_b32 s42, s35, 0x10000
	s_xor_b32 s100, s42, 0x10000
	v_add3_u32 v190, s100, v136, v161
	v_add3_u32 v194, s100, v142, v163
	ds_read_b128 v[190:193], v190
	v_add3_u32 v198, s100, v143, v159
	ds_read_b128 v[194:197], v194
	v_add3_u32 v202, s100, v152, v160
	ds_read_b128 v[198:201], v198 offset:32768
	v_add3_u32 v206, s100, v153, v157
	ds_read_b128 v[202:205], v202 offset:32768
	v_add3_u32 v210, s100, v156, v158
	ds_read_b128 v[206:209], v206 offset:32768
	ds_read_b128 v[210:213], v210 offset:32768
	s_waitcnt lgkmcnt(6)
	s_mov_b32 m0, s41
	v_lshl_add_u64 v[228:229], v[214:215], 0, s[28:29]
	v_mfma_f32_32x32x16_bf16 v[114:129], v[166:169], v[174:177], v[114:129]
	global_load_lds_dwordx4 v[228:229], off
	s_add_i32 m0, s41, 0x2000
	v_lshl_add_u64 v[228:229], v[214:215], 0, s[24:25]
	v_mfma_f32_32x32x16_bf16 v[98:113], v[166:169], v[178:181], v[98:113]
	v_mfma_f32_32x32x16_bf16 v[82:97], v[166:169], v[182:185], v[82:97]
	global_load_lds_dwordx4 v[228:229], off
	s_add_i32 m0, s41, 0x4000
	v_lshl_add_u64 v[228:229], v[214:215], 0, s[26:27]
	v_mfma_f32_32x32x16_bf16 v[66:81], v[166:169], v[186:189], v[66:81]
	v_mfma_f32_32x32x16_bf16 v[50:65], v[170:173], v[174:177], v[50:65]
	global_load_lds_dwordx4 v[228:229], off
	s_add_i32 m0, s41, 0x6000
	v_lshl_add_u64 v[228:229], v[214:215], 0, s[38:39]
	v_mfma_f32_32x32x16_bf16 v[34:49], v[170:173], v[178:181], v[34:49]
	v_mfma_f32_32x32x16_bf16 v[18:33], v[170:173], v[182:185], v[18:33]
	global_load_lds_dwordx4 v[228:229], off
	v_mfma_f32_32x32x16_bf16 v[2:17], v[170:173], v[186:189], v[2:17]
	v_add3_u32 v166, s100, v136, v149
	v_add3_u32 v170, s100, v142, v150
	ds_read_b128 v[166:169], v166
	v_add3_u32 v174, s100, v143, v147
	ds_read_b128 v[170:173], v170
	v_add3_u32 v178, s100, v152, v148
	ds_read_b128 v[174:177], v174 offset:32768
	v_add3_u32 v182, s100, v153, v145
	ds_read_b128 v[178:181], v178 offset:32768
	v_add3_u32 v186, s100, v156, v146
	ds_read_b128 v[182:185], v182 offset:32768
	ds_read_b128 v[186:189], v186 offset:32768
	s_waitcnt lgkmcnt(6)
	v_mfma_f32_32x32x16_bf16 v[114:129], v[190:193], v[198:201], v[114:129]
	v_mfma_f32_32x32x16_bf16 v[98:113], v[190:193], v[202:205], v[98:113]
	v_mfma_f32_32x32x16_bf16 v[82:97], v[190:193], v[206:209], v[82:97]
	v_mfma_f32_32x32x16_bf16 v[66:81], v[190:193], v[210:213], v[66:81]
	v_mfma_f32_32x32x16_bf16 v[50:65], v[194:197], v[198:201], v[50:65]
	v_mfma_f32_32x32x16_bf16 v[34:49], v[194:197], v[202:205], v[34:49]
	v_mfma_f32_32x32x16_bf16 v[18:33], v[194:197], v[206:209], v[18:33]
	v_mfma_f32_32x32x16_bf16 v[2:17], v[194:197], v[210:213], v[2:17]
	v_add3_u32 v190, s100, v136, v139
	v_add3_u32 v194, s100, v142, v140
	ds_read_b128 v[190:193], v190
	v_add3_u32 v198, s100, v143, v137
	ds_read_b128 v[194:197], v194
	v_add3_u32 v202, s100, v152, v138
	ds_read_b128 v[198:201], v198 offset:32768
	v_add3_u32 v206, s100, v153, v134
	ds_read_b128 v[202:205], v202 offset:32768
	v_add3_u32 v210, s100, v156, v135
	ds_read_b128 v[206:209], v206 offset:32768
	ds_read_b128 v[210:213], v210 offset:32768
	s_waitcnt lgkmcnt(6)
	v_mfma_f32_32x32x16_bf16 v[114:129], v[166:169], v[174:177], v[114:129]
	v_mfma_f32_32x32x16_bf16 v[98:113], v[166:169], v[178:181], v[98:113]
	v_mfma_f32_32x32x16_bf16 v[82:97], v[166:169], v[182:185], v[82:97]
	v_mfma_f32_32x32x16_bf16 v[66:81], v[166:169], v[186:189], v[66:81]
	v_mfma_f32_32x32x16_bf16 v[50:65], v[170:173], v[174:177], v[50:65]
	v_mfma_f32_32x32x16_bf16 v[34:49], v[170:173], v[178:181], v[34:49]
	v_mfma_f32_32x32x16_bf16 v[18:33], v[170:173], v[182:185], v[18:33]
	v_mfma_f32_32x32x16_bf16 v[2:17], v[170:173], v[186:189], v[2:17]
	s_add_u32 s30, s30, 0x80
	s_addc_u32 s31, s31, 0
	s_add_i32 s35, s35, 0x10000
	s_waitcnt vmcnt(0) lgkmcnt(0)
	s_barrier
	s_cmpk_lg_i32 s30, 0x780
	s_cbranch_scc0 .Lk627_exit
	s_add_i32 s41, s100, s34
	v_lshl_add_u64 v[214:215], v[130:131], 0, s[30:31]
	v_lshl_add_u64 v[226:227], v[132:133], 0, s[30:31]
	s_add_i32 m0, s41, 0x8000
	v_lshl_add_u64 v[228:229], v[226:227], 0, s[28:29]
	v_mfma_f32_32x32x16_bf16 v[114:129], v[190:193], v[198:201], v[114:129]
	global_load_lds_dwordx4 v[228:229], off
	s_add_i32 m0, s41, 0xa000
	v_lshl_add_u64 v[228:229], v[226:227], 0, s[24:25]
	v_mfma_f32_32x32x16_bf16 v[98:113], v[190:193], v[202:205], v[98:113]
	v_mfma_f32_32x32x16_bf16 v[82:97], v[190:193], v[206:209], v[82:97]
	global_load_lds_dwordx4 v[228:229], off
	v_add3_u32 v166, s42, v136, v141
	v_add3_u32 v170, s42, v142, v144
	ds_read_b128 v[166:169], v166
	v_add3_u32 v174, s42, v143, v151
	ds_read_b128 v[170:173], v170
	v_add3_u32 v178, s42, v152, v154
	ds_read_b128 v[174:177], v174 offset:32768
	v_add3_u32 v182, s42, v153, v155
	ds_read_b128 v[178:181], v178 offset:32768
	v_add3_u32 v186, s42, v156, v164
	ds_read_b128 v[182:185], v182 offset:32768
	ds_read_b128 v[186:189], v186 offset:32768
	s_add_i32 m0, s41, 0xc000
	v_lshl_add_u64 v[228:229], v[226:227], 0, s[26:27]
	v_mfma_f32_32x32x16_bf16 v[66:81], v[190:193], v[210:213], v[66:81]
	v_mfma_f32_32x32x16_bf16 v[50:65], v[194:197], v[198:201], v[50:65]
	global_load_lds_dwordx4 v[228:229], off
	s_add_i32 m0, s41, 0xe000
	v_lshl_add_u64 v[228:229], v[226:227], 0, s[38:39]
	v_mfma_f32_32x32x16_bf16 v[34:49], v[194:197], v[202:205], v[34:49]
	v_mfma_f32_32x32x16_bf16 v[18:33], v[194:197], v[206:209], v[18:33]
	global_load_lds_dwordx4 v[228:229], off
	v_mfma_f32_32x32x16_bf16 v[2:17], v[194:197], v[210:213], v[2:17]
	s_branch .LBB0_627
